# attention loops: canonicalising v_max x,x around row-max reductions dropped (on top of the dilated-loop changes)
# baseline (speedup 1.0000x reference)
.LBB0_662:
	s_abs_i32 s1, s44
	s_mul_hi_u32 s2, s1, s26
	s_mul_i32 s3, s2, s22
	s_ashr_i32 s0, s44, 31
	s_sub_i32 s1, s1, s3
	s_xor_b32 s0, s0, s25
	s_add_i32 s3, s2, 1
	s_sub_i32 s6, s1, s22
	s_cmp_ge_u32 s1, s22
	s_cselect_b32 s2, s3, s2
	s_cselect_b32 s1, s6, s1
	s_add_i32 s3, s2, 1
	s_cmp_ge_u32 s1, s22
	s_cselect_b32 s1, s3, s2
	s_xor_b32 s1, s1, s0
	s_sub_i32 s2, s1, s0
	s_lshl_b32 s2, s2, 1
	s_add_i32 s2, s2, s44
	s_and_b32 s45, s2, 7
	s_ashr_i32 s2, s44, 7
	s_ashr_i32 s3, s2, 31
	s_min_u32 s46, s45, 4
	s_lshl_b64 s[10:11], s[2:3], 12
	s_add_i32 s65, s46, 1
	s_lshl_b32 s3, s45, 5
	s_lshl_b32 s47, s65, 1
	s_sub_i32 s6, s3, 32
	s_cmp_eq_u32 s45, 0
	v_or_b32_e32 v0, s3, v199
	s_cselect_b32 s2, 4, 8
	s_cselect_b32 s13, 16, 20
	s_cselect_b32 s16, s23, s19
	s_cselect_b32 s17, 0, s6
	s_lshl_b32 s6, s44, 3
	v_lshl_add_u32 v16, v0, 4, s19
	s_and_b32 s48, s6, 0x3c0
	v_lshl_add_u64 v[0:1], s[10:11], 0, v[16:17]
	v_add_u32_e32 v8, 0x80, v16
	v_mov_b32_e32 v9, v17
	v_add_u32_e32 v18, 0x100, v16
	v_mov_b32_e32 v19, v17
	v_add_u32_e32 v16, 0x180, v16
	v_or_b32_e32 v64, s48, v210
	v_lshl_add_u64 v[8:9], s[10:11], 0, v[8:9]
	v_lshl_add_u64 v[18:19], s[10:11], 0, v[18:19]
	v_lshl_add_u64 v[26:27], s[10:11], 0, v[16:17]
	v_lshlrev_b64 v[0:1], 11, v[0:1]
	v_lshlrev_b32_e32 v58, 1, v64
	v_lshlrev_b64 v[8:9], 11, v[8:9]
	v_lshlrev_b64 v[18:19], 11, v[18:19]
	v_lshlrev_b64 v[26:27], 11, v[26:27]
	v_or_b32_e32 v0, v0, v58
	v_or_b32_e32 v8, v8, v58
	v_or_b32_e32 v18, v18, v58
	v_or_b32_e32 v26, v26, v58
	v_lshl_add_u64 v[2:3], s[40:41], 0, v[0:1]
	v_lshl_add_u64 v[4:5], s[42:43], 0, v[0:1]
	v_lshl_add_u64 v[10:11], s[40:41], 0, v[8:9]
	v_lshl_add_u64 v[12:13], s[42:43], 0, v[8:9]
	v_lshl_add_u64 v[20:21], s[40:41], 0, v[18:19]
	v_lshl_add_u64 v[22:23], s[42:43], 0, v[18:19]
	v_lshl_add_u64 v[28:29], s[40:41], 0, v[26:27]
	global_load_dwordx4 v[0:3], v[2:3], off
	s_nop 0
	global_load_dwordx4 v[4:7], v[4:5], off
	s_nop 0
	global_load_dwordx4 v[8:11], v[10:11], off
	s_nop 0
	global_load_dwordx4 v[12:15], v[12:13], off
	s_nop 0
	global_load_dwordx4 v[18:21], v[20:21], off
	s_nop 0
	global_load_dwordx4 v[22:25], v[22:23], off
	v_lshl_add_u64 v[30:31], s[42:43], 0, v[26:27]
	global_load_dwordx4 v[26:29], v[28:29], off
	s_nop 0
	global_load_dwordx4 v[48:51], v[30:31], off
	s_lshl_b32 s12, s45, 9
	s_or_b32 s14, s10, s12
	s_mov_b32 s15, s11
	v_lshl_add_u64 v[30:31], s[14:15], 0, v[202:203]
	s_lshl_b32 s6, s48, 1
	v_lshl_add_u64 v[52:53], v[200:201], 0, s[6:7]
	v_lshlrev_b64 v[206:207], 11, v[30:31]
	v_lshl_add_u64 v[30:31], v[52:53], 0, v[206:207]
	global_load_dwordx4 v[128:131], v[30:31], off
	global_load_dwordx4 v[132:135], v[30:31], off offset:32
	global_load_dwordx4 v[136:139], v[30:31], off offset:64
	global_load_dwordx4 v[140:143], v[30:31], off offset:96
	v_or_b32_e32 v16, s17, v199
	v_lshl_add_u32 v52, v16, 4, s16
	v_ashrrev_i32_e32 v53, 31, v52
	v_lshl_add_u64 v[54:55], s[10:11], 0, v[52:53]
	v_lshlrev_b64 v[54:55], 11, v[54:55]
	v_lshl_add_u64 v[56:57], v[30:31], 0, s[8:9]
	v_add_co_u32_e32 v30, vcc, s27, v30
	v_or_b32_e32 v54, v54, v58
	s_nop 0
	v_addc_co_u32_e32 v31, vcc, 0, v31, vcc
	global_load_dwordx4 v[144:147], v[56:57], off offset:32
	global_load_dwordx4 v[148:151], v[56:57], off offset:64
	global_load_dwordx4 v[152:155], v[30:31], off
	global_load_dwordx4 v[156:159], v[56:57], off offset:96
	s_lshl_b32 s1, s1, 1
	s_add_i32 s1, s29, s1
	s_lshl_b32 s0, s0, 1
	s_sub_i32 s0, s1, s0
	s_and_b32 s0, s0, 7
	v_or_b32_e32 v220, s3, v197
	s_min_u32 s3, s0, 4
	s_or_b32 s51, s12, 0x1e0
	v_add_u32_e32 v221, s12, v202
	v_add_u32_e32 v223, s12, v214
	s_lshl_b32 s1, s0, 9
	s_lshl_b32 s12, s3, 6
	s_add_i32 s6, s47, s2
	s_or_b32 s1, s1, s12
	s_lshl_b32 s2, s2, 5
	s_add_i32 s49, s6, s13
	s_waitcnt vmcnt(15)
	ds_write_b128 v215, v[0:3]
	s_waitcnt vmcnt(14)
	ds_write_b128 v216, v[4:7] offset:4608
	s_waitcnt vmcnt(13)
	ds_write_b128 v215, v[8:11] offset:1152
	s_waitcnt vmcnt(12)
	ds_write_b128 v216, v[12:15] offset:5120
	s_waitcnt vmcnt(11)
	ds_write_b128 v215, v[18:21] offset:2304
	s_waitcnt vmcnt(10)
	ds_write_b128 v216, v[22:25] offset:5632
	s_waitcnt vmcnt(9)
	ds_write_b128 v215, v[26:29] offset:3456
	s_waitcnt vmcnt(8)
	ds_write_b128 v216, v[48:51] offset:6144
	v_lshl_add_u64 v[0:1], s[40:41], 0, v[54:55]
	v_lshl_add_u64 v[2:3], s[42:43], 0, v[54:55]
	global_load_dwordx4 v[160:163], v[0:1], off
	global_load_dwordx4 v[164:167], v[2:3], off
	v_add_u32_e32 v0, 0x80, v52
	v_ashrrev_i32_e32 v1, 31, v0
	v_lshl_add_u64 v[0:1], s[10:11], 0, v[0:1]
	v_lshlrev_b64 v[0:1], 11, v[0:1]
	v_or_b32_e32 v0, v0, v58
	v_lshl_add_u64 v[2:3], s[40:41], 0, v[0:1]
	v_lshl_add_u64 v[0:1], s[42:43], 0, v[0:1]
	global_load_dwordx4 v[168:171], v[2:3], off
	global_load_dwordx4 v[172:175], v[0:1], off
	v_add_u32_e32 v0, 0x100, v52
	v_ashrrev_i32_e32 v1, 31, v0
	v_lshl_add_u64 v[0:1], s[10:11], 0, v[0:1]
	v_lshlrev_b64 v[0:1], 11, v[0:1]
	v_or_b32_e32 v0, v0, v58
	v_lshl_add_u64 v[2:3], s[40:41], 0, v[0:1]
	v_lshl_add_u64 v[0:1], s[42:43], 0, v[0:1]
	global_load_dwordx4 v[176:179], v[2:3], off
	global_load_dwordx4 v[180:183], v[0:1], off
	v_add_u32_e32 v0, 0x180, v52
	v_ashrrev_i32_e32 v1, 31, v0
	v_lshl_add_u64 v[0:1], s[10:11], 0, v[0:1]
	v_lshlrev_b64 v[0:1], 11, v[0:1]
	v_or_b32_e32 v0, v0, v58
	v_lshl_add_u64 v[2:3], s[40:41], 0, v[0:1]
	v_lshl_add_u64 v[0:1], s[42:43], 0, v[0:1]
	global_load_dwordx4 v[184:187], v[2:3], off
	global_load_dwordx4 v[188:191], v[0:1], off
	s_waitcnt lgkmcnt(0)
	ds_read_b128 v[18:21], v217
	ds_read_b128 v[22:25], v217 offset:32
	s_waitcnt vmcnt(15) lgkmcnt(1)
	v_mfma_f32_32x32x16_bf16 v[0:15], v[18:21], v[128:131], v[32:47]
	ds_read_b128 v[18:21], v217 offset:64
	s_lshl_b32 s13, s45, 7
	s_add_i32 s1, s1, s2
	s_lshl_b32 s0, s0, 5
	v_lshlrev_b32_e32 v225, 1, v64
	s_sub_i32 s50, -2, s46
	s_or_b32 s64, s13, 0x60
	s_waitcnt vmcnt(14) lgkmcnt(1)
	v_mfma_f32_32x32x16_bf16 v[0:15], v[22:25], v[132:135], v[0:15]
	s_add_i32 s65, s65, s45
	v_add_u32_e32 v205, s13, v212
	v_add_u32_e32 v222, s13, v213
	s_add_i32 s66, s1, 0x200
	s_sub_i32 s67, s0, 32
	s_lshl_b32 s68, s3, 5
	v_mov_b32_e32 v219, 0
	s_waitcnt vmcnt(13) lgkmcnt(0)
	v_mfma_f32_32x32x16_bf16 v[0:15], v[18:21], v[136:139], v[0:15]
	ds_read_b128 v[18:21], v217 offset:96
	s_mov_b32 s70, 1
	v_mov_b32_e32 v226, 0
	s_waitcnt vmcnt(12) lgkmcnt(0)
	v_mfma_f32_32x32x16_bf16 v[0:15], v[18:21], v[140:143], v[0:15]
	s_nop 11
	v_max_f32_e32 v16, v0, v1
	v_max3_f32 v16, v16, v2, v3
	v_max3_f32 v16, v16, v4, v5
	v_max3_f32 v16, v16, v6, v7
	v_max3_f32 v16, v16, v8, v9
	v_max3_f32 v16, v16, v10, v11
	v_max3_f32 v16, v16, v12, v13
	v_max3_f32 v16, v16, v14, v15
	v_mov_b32_e32 v18, v16
	s_nop 1
	v_permlane32_swap_b32_e32 v16, v18
	v_max_f32_e32 v18, v18, v18
	v_max_f32_e32 v16, v16, v16
	v_max_f32_e32 v23, v16, v18
	v_exp_f32_e64 v16, -v23
	v_sub_f32_e32 v15, v15, v23
	v_sub_f32_e32 v14, v14, v23
	v_sub_f32_e32 v13, v13, v23
	v_sub_f32_e32 v12, v12, v23
	v_sub_f32_e32 v11, v11, v23
	v_sub_f32_e32 v10, v10, v23
	v_sub_f32_e32 v9, v9, v23
	v_sub_f32_e32 v8, v8, v23
	v_sub_f32_e32 v7, v7, v23
	v_sub_f32_e32 v6, v6, v23
	v_sub_f32_e32 v5, v5, v23
	v_sub_f32_e32 v4, v4, v23
	v_sub_f32_e32 v3, v3, v23
	v_sub_f32_e32 v2, v2, v23
	v_sub_f32_e32 v1, v1, v23
	v_sub_f32_e32 v0, v0, v23
	v_exp_f32_e32 v25, v0
	v_exp_f32_e32 v24, v1
	v_exp_f32_e32 v27, v2
	v_exp_f32_e32 v26, v3
	v_exp_f32_e32 v29, v4
	v_exp_f32_e32 v28, v5
	v_exp_f32_e32 v31, v6
	v_exp_f32_e32 v30, v7
	v_exp_f32_e32 v67, v8
	v_exp_f32_e32 v66, v9
	v_exp_f32_e32 v69, v10
	v_exp_f32_e32 v68, v11
	v_exp_f32_e32 v71, v12
	v_exp_f32_e32 v70, v13
	v_exp_f32_e32 v73, v14
	v_exp_f32_e32 v72, v15
	v_cvt_pk_bf16_f32 v0, v25, v24
	v_cvt_pk_bf16_f32 v1, v27, v26
	v_cvt_pk_bf16_f32 v2, v29, v28
	v_cvt_pk_bf16_f32 v3, v31, v30
	v_cvt_pk_bf16_f32 v4, v67, v66
	v_cvt_pk_bf16_f32 v5, v69, v68
	v_cvt_pk_bf16_f32 v6, v71, v70
	v_cvt_pk_bf16_f32 v7, v73, v72
	ds_read_b64_tr_b16 v[8:9], v218 offset:4608
	ds_read_b64_tr_b16 v[10:11], v218 offset:5120
	ds_read_b64_tr_b16 v[12:13], v218 offset:5632
	ds_read_b64_tr_b16 v[14:15], v218 offset:6144
	ds_read_b64_tr_b16 v[18:19], v218 offset:6656
	ds_read_b64_tr_b16 v[20:21], v218 offset:7168
	v_mul_f32_e32 v48, 0, v16
	v_mov_b32_e32 v49, v48
	v_mov_b32_e32 v50, v48
	v_mov_b32_e32 v51, v48
	v_mov_b32_e32 v52, v48
	v_mov_b32_e32 v53, v48
	v_mov_b32_e32 v54, v48
	v_mov_b32_e32 v55, v48
	v_mov_b32_e32 v56, v48
	v_mov_b32_e32 v57, v48
	v_mov_b32_e32 v58, v48
	v_mov_b32_e32 v59, v48
	v_mov_b32_e32 v60, v48
	v_mov_b32_e32 v61, v48
	v_mov_b32_e32 v62, v48
	v_mov_b32_e32 v63, v48
	v_mov_b32_e32 v22, v48
	v_mov_b32_e32 v16, v17
	s_waitcnt lgkmcnt(4)
	v_mfma_f32_32x32x16_bf16 v[96:111], v[8:11], v[0:3], v[48:63]
	ds_read_b64_tr_b16 v[8:9], v218 offset:7680
	ds_read_b64_tr_b16 v[10:11], v218 offset:8192
	s_waitcnt lgkmcnt(0)
	s_waitcnt lgkmcnt(2)
	v_mfma_f32_32x32x16_bf16 v[48:63], v[18:21], v[0:3], v[48:63]
	v_add_f32_e64 v0, v24, 0
	v_add_f32_e64 v1, v25, 0
	v_mov_b32_e32 v18, v17
	v_add_f32_e64 v0, v26, v0
	v_add_f32_e64 v1, v27, v1
	v_mov_b32_e32 v19, v17
	v_pk_add_f32 v[0:1], v[28:29], v[0:1]
	v_mov_b32_e32 v20, v17
	v_pk_add_f32 v[0:1], v[30:31], v[0:1]
	v_mfma_f32_32x32x16_bf16 v[96:111], v[12:15], v[4:7], v[96:111]
	v_add_f32_e64 v0, v66, v0
	v_add_f32_e64 v1, v67, v1
	v_mov_b32_e32 v30, v17
	v_add_f32_e64 v0, v68, v0
	v_add_f32_e64 v1, v69, v1
	v_mov_b32_e32 v31, v17
	v_pk_add_f32 v[0:1], v[70:71], v[0:1]
	v_mov_b32_e32 v21, v17
	v_pk_add_f32 v[0:1], v[72:73], v[0:1]
	s_waitcnt lgkmcnt(0)
	v_mfma_f32_32x32x16_bf16 v[48:63], v[8:11], v[4:7], v[48:63]
	v_pk_add_f32 v[0:1], v[0:1], v[0:1] op_sel:[0,1] op_sel_hi:[1,0]
	v_mov_b32_e32 v24, v17
	v_mov_b32_e32 v1, v17
	v_pk_add_f32 v[208:209], v[22:23], v[0:1]
	v_mov_b32_e32 v22, v17
	v_mov_b32_e32 v23, v17
	v_mov_b32_e32 v25, v17
	v_mov_b32_e32 v26, v17
	v_mov_b32_e32 v27, v17
	v_mov_b32_e32 v28, v17
	v_mov_b32_e32 v29, v17
	v_mov_b64_e32 v[78:79], v[30:31]
	v_mov_b64_e32 v[94:95], v[30:31]
	v_mov_b64_e32 v[76:77], v[28:29]
	v_mov_b64_e32 v[74:75], v[26:27]
	v_mov_b64_e32 v[72:73], v[24:25]
	v_mov_b64_e32 v[70:71], v[22:23]
	v_mov_b64_e32 v[68:69], v[20:21]
	v_mov_b64_e32 v[66:67], v[18:19]
	v_mov_b64_e32 v[64:65], v[16:17]
	v_mov_b64_e32 v[92:93], v[28:29]
	v_mov_b64_e32 v[90:91], v[26:27]
	v_mov_b64_e32 v[88:89], v[24:25]
	v_mov_b64_e32 v[86:87], v[22:23]
	v_mov_b64_e32 v[84:85], v[20:21]
	v_mov_b64_e32 v[82:83], v[18:19]
	v_mov_b64_e32 v[80:81], v[16:17]

.LBB0_708:
	s_nop 7
	s_waitcnt lgkmcnt(0)
	v_max_f32_e32 v16, v0, v1
	v_max3_f32 v16, v16, v2, v3
	v_max3_f32 v16, v16, v4, v5
	v_max3_f32 v16, v16, v6, v7
	v_max3_f32 v16, v16, v8, v9
	v_max3_f32 v16, v16, v10, v11
	v_max3_f32 v16, v16, v12, v13
	v_max3_f32 v16, v16, v14, v15
	v_mov_b32_e32 v18, v16
	s_nop 1
	v_permlane32_swap_b32_e32 v16, v18
	v_max_f32_e32 v16, v16, v18
	v_cmp_lt_f32_e32 vcc, s28, v16
	s_cbranch_vccnz .Ldd_rescA

.LBB0_718:
	v_max_f32_e32 v16, v112, v113
	v_max3_f32 v16, v16, v114, v115
	v_max3_f32 v16, v16, v116, v117
	v_max3_f32 v16, v16, v118, v119
	v_max3_f32 v16, v16, v120, v121
	v_max3_f32 v16, v16, v122, v123
	v_max3_f32 v16, v16, v124, v125
	v_max3_f32 v16, v16, v126, v127
	v_mov_b32_e32 v18, v16
	s_nop 1
	v_permlane32_swap_b32_e32 v16, v18
	s_cmp_eq_u32 s68, 0
	s_cselect_b64 s[0:1], -1, 0
	v_max_f32_e32 v16, v16, v18
	s_cbranch_scc1 .Ldd_rescB
	v_cmp_lt_f32_e32 vcc, s28, v16
	s_cbranch_vccnz .Ldd_rescB

.LBB0_1918:
	s_nop 10
	v_max_f32_e32 v1, v32, v33
	v_max3_f32 v1, v1, v34, v35
	v_max3_f32 v1, v1, v36, v37
	v_max3_f32 v1, v1, v38, v39
	v_max3_f32 v1, v1, v40, v41
	v_max3_f32 v1, v1, v42, v43
	v_max3_f32 v1, v1, v44, v45
	v_max3_f32 v1, v1, v46, v47
	v_mov_b32_e32 v2, v1
	s_nop 1
	v_permlane32_swap_b32_e32 v1, v2
	v_max_f32_e32 v1, v1, v2
	v_exp_f32_e64 v15, -v1
	v_sub_f32_e32 v2, v32, v1
	v_sub_f32_e32 v3, v33, v1
	v_sub_f32_e32 v4, v34, v1
	v_sub_f32_e32 v5, v35, v1
	v_sub_f32_e32 v6, v36, v1
	v_sub_f32_e32 v7, v37, v1
	v_sub_f32_e32 v8, v38, v1
	v_sub_f32_e32 v9, v39, v1
	v_sub_f32_e32 v10, v40, v1
	v_sub_f32_e32 v11, v41, v1
	v_sub_f32_e32 v12, v42, v1
	v_sub_f32_e32 v13, v43, v1
	v_sub_f32_e32 v14, v44, v1
	v_sub_f32_e32 v32, v45, v1
	v_sub_f32_e32 v33, v46, v1
	v_sub_f32_e32 v34, v47, v1
	v_add_u32_e32 v241, v234, v228
	v_exp_f32_e32 v163, v2
	v_exp_f32_e32 v162, v3
	v_exp_f32_e32 v161, v4
	v_exp_f32_e32 v160, v5
	v_exp_f32_e32 v127, v6
	v_exp_f32_e32 v126, v7
	v_exp_f32_e32 v125, v8
	v_exp_f32_e32 v124, v9
	v_exp_f32_e32 v123, v10
	v_exp_f32_e32 v122, v11
	v_exp_f32_e32 v121, v12
	v_exp_f32_e32 v120, v13
	v_exp_f32_e32 v119, v14
	v_exp_f32_e32 v118, v32
	v_exp_f32_e32 v117, v33
	v_exp_f32_e32 v116, v34
	v_cvt_pk_bf16_f32 v32, v163, v162
	v_cvt_pk_bf16_f32 v33, v161, v160
	v_cvt_pk_bf16_f32 v34, v127, v126
	v_cvt_pk_bf16_f32 v35, v125, v124
	v_cvt_pk_bf16_f32 v36, v123, v122
	v_cvt_pk_bf16_f32 v37, v121, v120
	v_cvt_pk_bf16_f32 v38, v119, v118
	v_cvt_pk_bf16_f32 v39, v117, v116
	ds_read_b64_tr_b16 v[10:11], v241 offset:4608
	ds_read_b64_tr_b16 v[12:13], v241 offset:5120
	v_mul_f32_e32 v96, 0, v15
	v_mov_b32_e32 v97, v96
	ds_read_b64_tr_b16 v[2:3], v241 offset:5632
	ds_read_b64_tr_b16 v[4:5], v241 offset:6144
	ds_read_b64_tr_b16 v[112:113], v241 offset:6656
	ds_read_b64_tr_b16 v[114:115], v241 offset:7168
	ds_read_b64_tr_b16 v[6:7], v241 offset:7680
	ds_read_b64_tr_b16 v[8:9], v241 offset:8192
	v_mov_b32_e32 v98, v96
	v_mov_b32_e32 v99, v96
	v_mov_b32_e32 v100, v96
	v_mov_b32_e32 v101, v96
	v_mov_b32_e32 v102, v96
	v_mov_b32_e32 v103, v96
	v_mov_b32_e32 v104, v96
	v_mov_b32_e32 v105, v96
	v_mov_b32_e32 v106, v96
	v_mov_b32_e32 v107, v96
	v_mov_b32_e32 v108, v96
	v_mov_b32_e32 v109, v96
	v_mov_b32_e32 v110, v96
	v_mov_b32_e32 v111, v96
	v_mov_b64_e32 v[64:65], v[96:97]
	v_mov_b64_e32 v[66:67], v[98:99]
	v_mov_b64_e32 v[68:69], v[100:101]
	v_mov_b64_e32 v[70:71], v[102:103]
	v_mov_b64_e32 v[72:73], v[104:105]
	v_mov_b64_e32 v[74:75], v[106:107]
	v_mov_b64_e32 v[76:77], v[108:109]
	v_mov_b64_e32 v[78:79], v[110:111]
	s_waitcnt lgkmcnt(6)
	v_mfma_f32_32x32x16_bf16 v[48:63], v[10:13], v[32:35], v[96:111]
	s_waitcnt lgkmcnt(0)
	s_and_b64 vcc, exec, s[20:21]
	s_waitcnt lgkmcnt(2)
	v_mfma_f32_32x32x16_bf16 v[64:79], v[112:115], v[32:35], v[64:79]
	v_mfma_f32_32x32x16_bf16 v[48:63], v[2:5], v[36:39], v[48:63]
	s_waitcnt lgkmcnt(0)
	v_mfma_f32_32x32x16_bf16 v[64:79], v[6:9], v[36:39], v[64:79]
	s_cbranch_vccz .LBB0_1920
	v_max_f32_e32 v14, v80, v81
	v_max3_f32 v14, v14, v82, v83
	v_max3_f32 v14, v14, v84, v85
	v_max3_f32 v14, v14, v86, v87
	v_max3_f32 v14, v14, v88, v89
	v_max3_f32 v14, v14, v90, v91
	v_max3_f32 v14, v14, v92, v93
	v_max3_f32 v14, v14, v94, v95
	v_mov_b32_e32 v15, v14
	s_nop 1
	v_permlane32_swap_b32_e32 v14, v15
	v_max_f32_e32 v15, v15, v15
	v_max_f32_e32 v14, v14, v14
	v_max_f32_e32 v15, v14, v15
	v_exp_f32_e64 v14, -v15
	v_sub_f32_e32 v90, v90, v15
	v_sub_f32_e32 v89, v89, v15
	v_sub_f32_e32 v88, v88, v15
	v_mul_f32_e32 v32, 0, v14
	v_mov_b32_e32 v33, v32
	v_mov_b32_e32 v34, v32
	v_mov_b32_e32 v35, v32
	v_mov_b32_e32 v36, v32
	v_mov_b32_e32 v37, v32
	v_mov_b32_e32 v38, v32
	v_mov_b32_e32 v39, v32
	v_mov_b32_e32 v40, v32
	v_mov_b32_e32 v41, v32
	v_mov_b32_e32 v42, v32
	v_mov_b32_e32 v43, v32
	v_mov_b32_e32 v44, v32
	v_mov_b32_e32 v45, v32
	v_mov_b32_e32 v46, v32
	v_mov_b32_e32 v47, v32
	v_sub_f32_e32 v14, v95, v15
	v_sub_f32_e32 v87, v87, v15
	v_sub_f32_e32 v86, v86, v15
	v_sub_f32_e32 v85, v85, v15
	v_sub_f32_e32 v84, v84, v15
	v_sub_f32_e32 v83, v83, v15
	v_sub_f32_e32 v82, v82, v15
	v_sub_f32_e32 v81, v81, v15
	v_sub_f32_e32 v80, v80, v15
	v_sub_f32_e32 v97, v94, v15
	v_sub_f32_e32 v240, v93, v15
	v_sub_f32_e32 v245, v92, v15
	v_sub_f32_e32 v246, v91, v15
	v_exp_f32_e32 v103, v80
	v_exp_f32_e32 v102, v81
	v_exp_f32_e32 v105, v82
	v_exp_f32_e32 v104, v83
	v_exp_f32_e32 v107, v84
	v_exp_f32_e32 v106, v85
	v_exp_f32_e32 v109, v86
	v_exp_f32_e32 v108, v87
	v_exp_f32_e32 v111, v88
	v_exp_f32_e32 v110, v89
	v_exp_f32_e32 v247, v90
	v_cvt_pk_bf16_f32 v98, v103, v102
	v_cvt_pk_bf16_f32 v99, v105, v104
	v_cvt_pk_bf16_f32 v100, v107, v106
	v_cvt_pk_bf16_f32 v101, v109, v108
	v_exp_f32_e32 v250, v14
	v_mfma_f32_32x32x16_bf16 v[80:95], v[10:13], v[98:101], v[32:47]
	v_mov_b32_e32 v14, v32
	v_add_f32_e64 v10, v102, 0
	v_add_f32_e64 v11, v103, 0
	v_exp_f32_e32 v246, v246
	v_pk_add_f32 v[10:11], v[104:105], v[10:11]
	v_exp_f32_e32 v249, v245
	v_exp_f32_e32 v248, v240
	v_pk_add_f32 v[10:11], v[106:107], v[10:11]
	v_mfma_f32_32x32x16_bf16 v[32:47], v[112:115], v[98:101], v[32:47]
	v_exp_f32_e32 v251, v97
	v_pk_add_f32 v[98:99], v[108:109], v[10:11]
	v_cvt_pk_bf16_f32 v10, v111, v110
	v_cvt_pk_bf16_f32 v11, v247, v246
	v_cvt_pk_bf16_f32 v12, v249, v248
	v_cvt_pk_bf16_f32 v13, v251, v250
	s_nop 0
	v_mfma_f32_32x32x16_bf16 v[80:95], v[2:5], v[10:13], v[80:95]
	v_add_f32_e64 v2, v110, v98
	v_add_f32_e64 v3, v111, v99
	v_add_f32_e64 v2, v246, v2
	v_add_f32_e64 v3, v247, v3
	v_add_f32_e64 v2, v248, v2
	v_add_f32_e64 v3, v249, v3
	v_pk_add_f32 v[2:3], v[250:251], v[2:3]
	v_mfma_f32_32x32x16_bf16 v[32:47], v[6:9], v[10:13], v[32:47]
	v_pk_add_f32 v[2:3], v[2:3], v[2:3] op_sel:[0,1] op_sel_hi:[1,0]
	s_nop 0
	v_mov_b32_e32 v3, v167
	v_pk_add_f32 v[14:15], v[14:15], v[2:3]
	s_branch .LBB0_1921

.LBB0_1927:
	v_max_f32_e32 v2, v112, v113
	v_max3_f32 v2, v2, v114, v115
	v_max3_f32 v2, v2, v116, v117
	v_max3_f32 v2, v2, v118, v119
	v_max3_f32 v2, v2, v120, v121
	v_max3_f32 v2, v2, v122, v123
	v_max3_f32 v2, v2, v124, v125
	v_max3_f32 v2, v2, v126, v127
	v_mov_b32_e32 v3, v2
	s_nop 1
	v_permlane32_swap_b32_e32 v2, v3
	v_max_f32_e32 v2, v2, v3
	v_cmp_lt_f32_e32 vcc, s88, v2
	s_cbranch_vccz .LBB0_1929
	v_max_f32_e32 v2, v2, v2
	v_max_f32_e32 v2, 0, v2
	v_exp_f32_e64 v4, -v2
	v_add_f32_e32 v1, v1, v2
	v_pk_add_f32 v[112:113], v[112:113], v[2:3] op_sel_hi:[1,0] neg_lo:[0,1] neg_hi:[0,1]
	v_pk_add_f32 v[114:115], v[114:115], v[2:3] op_sel_hi:[1,0] neg_lo:[0,1] neg_hi:[0,1]
	v_pk_add_f32 v[116:117], v[116:117], v[2:3] op_sel_hi:[1,0] neg_lo:[0,1] neg_hi:[0,1]
	v_pk_add_f32 v[118:119], v[118:119], v[2:3] op_sel_hi:[1,0] neg_lo:[0,1] neg_hi:[0,1]
	v_pk_add_f32 v[120:121], v[120:121], v[2:3] op_sel_hi:[1,0] neg_lo:[0,1] neg_hi:[0,1]
	v_pk_add_f32 v[122:123], v[122:123], v[2:3] op_sel_hi:[1,0] neg_lo:[0,1] neg_hi:[0,1]
	v_pk_add_f32 v[124:125], v[124:125], v[2:3] op_sel_hi:[1,0] neg_lo:[0,1] neg_hi:[0,1]
	v_pk_add_f32 v[126:127], v[126:127], v[2:3] op_sel_hi:[1,0] neg_lo:[0,1] neg_hi:[0,1]
	v_mul_f32_e32 v240, v240, v4
	v_pk_mul_f32 v[62:63], v[62:63], v[4:5] op_sel_hi:[1,0]
	v_pk_mul_f32 v[60:61], v[60:61], v[4:5] op_sel_hi:[1,0]
	v_pk_mul_f32 v[58:59], v[58:59], v[4:5] op_sel_hi:[1,0]
	v_pk_mul_f32 v[56:57], v[56:57], v[4:5] op_sel_hi:[1,0]
	v_pk_mul_f32 v[54:55], v[54:55], v[4:5] op_sel_hi:[1,0]
	v_pk_mul_f32 v[52:53], v[52:53], v[4:5] op_sel_hi:[1,0]
	v_pk_mul_f32 v[50:51], v[50:51], v[4:5] op_sel_hi:[1,0]
	v_pk_mul_f32 v[48:49], v[48:49], v[4:5] op_sel_hi:[1,0]
	v_pk_mul_f32 v[78:79], v[78:79], v[4:5] op_sel_hi:[1,0]
	v_pk_mul_f32 v[76:77], v[76:77], v[4:5] op_sel_hi:[1,0]
	v_pk_mul_f32 v[74:75], v[74:75], v[4:5] op_sel_hi:[1,0]
	v_pk_mul_f32 v[72:73], v[72:73], v[4:5] op_sel_hi:[1,0]
	v_pk_mul_f32 v[70:71], v[70:71], v[4:5] op_sel_hi:[1,0]
	v_pk_mul_f32 v[68:69], v[68:69], v[4:5] op_sel_hi:[1,0]
	v_pk_mul_f32 v[66:67], v[66:67], v[4:5] op_sel_hi:[1,0]
	v_pk_mul_f32 v[64:65], v[64:65], v[4:5] op_sel_hi:[1,0]
.LBB0_1929:
	v_exp_f32_e32 v160, v112
	v_exp_f32_e32 v161, v113
	v_exp_f32_e32 v162, v114
	v_exp_f32_e32 v163, v115
	v_exp_f32_e32 v116, v116
	v_exp_f32_e32 v117, v117
	v_exp_f32_e32 v118, v118
	v_exp_f32_e32 v119, v119
	v_exp_f32_e32 v120, v120
	v_exp_f32_e32 v121, v121
	v_exp_f32_e32 v122, v122
	v_exp_f32_e32 v123, v123
	v_exp_f32_e32 v124, v124
	v_exp_f32_e32 v125, v125
	v_exp_f32_e32 v126, v126
	v_exp_f32_e32 v127, v127
	v_cvt_pk_bf16_f32 v246, v160, v161
	v_cvt_pk_bf16_f32 v247, v162, v163
	v_cvt_pk_bf16_f32 v248, v116, v117
	v_cvt_pk_bf16_f32 v249, v118, v119
	v_cvt_pk_bf16_f32 v250, v120, v121
	v_cvt_pk_bf16_f32 v251, v122, v123
	v_cvt_pk_bf16_f32 v252, v124, v125
	v_cvt_pk_bf16_f32 v253, v126, v127
	ds_read_b64_tr_b16 v[10:11], v241 offset:4608
	ds_read_b64_tr_b16 v[12:13], v241 offset:5120
	ds_read_b64_tr_b16 v[2:3], v241 offset:5632
	ds_read_b64_tr_b16 v[4:5], v241 offset:6144
	ds_read_b64_tr_b16 v[112:113], v241 offset:6656
	ds_read_b64_tr_b16 v[114:115], v241 offset:7168
	ds_read_b64_tr_b16 v[6:7], v241 offset:7680
	ds_read_b64_tr_b16 v[8:9], v241 offset:8192
	s_waitcnt lgkmcnt(6)
	v_mfma_f32_32x32x16_bf16 v[48:63], v[10:13], v[246:249], v[48:63]
	s_waitcnt lgkmcnt(0)
	s_and_b64 vcc, exec, s[22:23]
	s_waitcnt lgkmcnt(2)
	v_mfma_f32_32x32x16_bf16 v[64:79], v[112:115], v[246:249], v[64:79]
	v_mfma_f32_32x32x16_bf16 v[48:63], v[2:5], v[250:253], v[48:63]
	s_waitcnt lgkmcnt(0)
	v_mfma_f32_32x32x16_bf16 v[64:79], v[6:9], v[250:253], v[64:79]
	s_cbranch_vccnz .LBB0_1923
	v_max_f32_e32 v245, v96, v97
	v_max3_f32 v245, v245, v98, v99
	v_max3_f32 v245, v245, v100, v101
	v_max3_f32 v245, v245, v102, v103
	v_max3_f32 v245, v245, v104, v105
	v_max3_f32 v245, v245, v106, v107
	v_max3_f32 v245, v245, v108, v109
	v_max3_f32 v245, v245, v110, v111
	v_mov_b32_e32 v246, v245
	s_nop 1
	v_permlane32_swap_b32_e32 v245, v246
	v_max_f32_e32 v245, v245, v246
	v_cmp_lt_f32_e32 vcc, s88, v245
	s_cbranch_vccz .LBB0_1922
	v_max_f32_e32 v245, v245, v245
	v_max_f32_e32 v246, 0, v245
	v_exp_f32_e64 v248, -v246
	v_add_f32_e32 v15, v15, v246
	v_pk_add_f32 v[96:97], v[96:97], v[246:247] op_sel_hi:[1,0] neg_lo:[0,1] neg_hi:[0,1]
	v_pk_add_f32 v[98:99], v[98:99], v[246:247] op_sel_hi:[1,0] neg_lo:[0,1] neg_hi:[0,1]
	v_pk_add_f32 v[100:101], v[100:101], v[246:247] op_sel_hi:[1,0] neg_lo:[0,1] neg_hi:[0,1]
	v_pk_add_f32 v[102:103], v[102:103], v[246:247] op_sel_hi:[1,0] neg_lo:[0,1] neg_hi:[0,1]
	v_pk_add_f32 v[104:105], v[104:105], v[246:247] op_sel_hi:[1,0] neg_lo:[0,1] neg_hi:[0,1]
	v_pk_add_f32 v[106:107], v[106:107], v[246:247] op_sel_hi:[1,0] neg_lo:[0,1] neg_hi:[0,1]
	v_pk_add_f32 v[108:109], v[108:109], v[246:247] op_sel_hi:[1,0] neg_lo:[0,1] neg_hi:[0,1]
	v_pk_add_f32 v[110:111], v[110:111], v[246:247] op_sel_hi:[1,0] neg_lo:[0,1] neg_hi:[0,1]
	v_mul_f32_e32 v14, v14, v248
	v_pk_mul_f32 v[94:95], v[94:95], v[248:249] op_sel_hi:[1,0]
	v_pk_mul_f32 v[92:93], v[92:93], v[248:249] op_sel_hi:[1,0]
	v_pk_mul_f32 v[90:91], v[90:91], v[248:249] op_sel_hi:[1,0]
	v_pk_mul_f32 v[88:89], v[88:89], v[248:249] op_sel_hi:[1,0]
	v_pk_mul_f32 v[86:87], v[86:87], v[248:249] op_sel_hi:[1,0]
	v_pk_mul_f32 v[84:85], v[84:85], v[248:249] op_sel_hi:[1,0]
	v_pk_mul_f32 v[82:83], v[82:83], v[248:249] op_sel_hi:[1,0]
	v_pk_mul_f32 v[80:81], v[80:81], v[248:249] op_sel_hi:[1,0]
	v_pk_mul_f32 v[46:47], v[46:47], v[248:249] op_sel_hi:[1,0]
	v_pk_mul_f32 v[44:45], v[44:45], v[248:249] op_sel_hi:[1,0]
	v_pk_mul_f32 v[42:43], v[42:43], v[248:249] op_sel_hi:[1,0]
	v_pk_mul_f32 v[40:41], v[40:41], v[248:249] op_sel_hi:[1,0]
	v_pk_mul_f32 v[38:39], v[38:39], v[248:249] op_sel_hi:[1,0]
	v_pk_mul_f32 v[36:37], v[36:37], v[248:249] op_sel_hi:[1,0]
	v_pk_mul_f32 v[34:35], v[34:35], v[248:249] op_sel_hi:[1,0]
	v_pk_mul_f32 v[32:33], v[32:33], v[248:249] op_sel_hi:[1,0]
	s_branch .LBB0_1922

.LBB0_1937:
	v_exp_f32_e32 v128, v112
	v_exp_f32_e32 v129, v113
	v_exp_f32_e32 v130, v114
	v_exp_f32_e32 v131, v115
	v_exp_f32_e32 v116, v116
	v_exp_f32_e32 v117, v117
	v_exp_f32_e32 v118, v118
	v_exp_f32_e32 v119, v119
	v_exp_f32_e32 v120, v120
	v_exp_f32_e32 v121, v121
	v_exp_f32_e32 v122, v122
	v_exp_f32_e32 v123, v123
	v_exp_f32_e32 v124, v124
	v_exp_f32_e32 v125, v125
	v_exp_f32_e32 v126, v126
	v_exp_f32_e32 v127, v127
	v_cvt_pk_bf16_f32 v132, v128, v129
	v_cvt_pk_bf16_f32 v133, v130, v131
	v_cvt_pk_bf16_f32 v134, v116, v117
	v_cvt_pk_bf16_f32 v135, v118, v119
	v_cvt_pk_bf16_f32 v136, v120, v121
	v_cvt_pk_bf16_f32 v137, v122, v123
	v_cvt_pk_bf16_f32 v138, v124, v125
	v_cvt_pk_bf16_f32 v139, v126, v127
	ds_read_b64_tr_b16 v[10:11], v241 offset:4608
	ds_read_b64_tr_b16 v[12:13], v241 offset:5120
	ds_read_b64_tr_b16 v[2:3], v241 offset:5632
	ds_read_b64_tr_b16 v[4:5], v241 offset:6144
	ds_read_b64_tr_b16 v[112:113], v241 offset:6656
	ds_read_b64_tr_b16 v[114:115], v241 offset:7168
	ds_read_b64_tr_b16 v[6:7], v241 offset:7680
	ds_read_b64_tr_b16 v[8:9], v241 offset:8192
	s_waitcnt lgkmcnt(6)
	v_mfma_f32_32x32x16_bf16 v[48:63], v[10:13], v[132:135], v[48:63]
	s_waitcnt lgkmcnt(0)
	s_and_b64 vcc, exec, s[22:23]
	s_waitcnt lgkmcnt(2)
	v_mfma_f32_32x32x16_bf16 v[64:79], v[112:115], v[132:135], v[64:79]
	v_mfma_f32_32x32x16_bf16 v[48:63], v[2:5], v[136:139], v[48:63]
	s_waitcnt lgkmcnt(0)
	v_mfma_f32_32x32x16_bf16 v[64:79], v[6:9], v[136:139], v[64:79]
	s_cbranch_vccnz .LBB0_1941
	v_max_f32_e32 v132, v96, v97
	v_max3_f32 v132, v132, v98, v99
	v_max3_f32 v132, v132, v100, v101
	v_max3_f32 v132, v132, v102, v103
	v_max3_f32 v132, v132, v104, v105
	v_max3_f32 v132, v132, v106, v107
	v_max3_f32 v132, v132, v108, v109
	v_max3_f32 v132, v132, v110, v111
	v_mov_b32_e32 v133, v132
	s_nop 1
	v_permlane32_swap_b32_e32 v132, v133
	v_max_f32_e32 v132, v132, v133
	v_cmp_lt_f32_e32 vcc, s88, v132
	s_cbranch_vccz .LBB0_1940
	v_max_f32_e32 v132, v132, v132
	v_max_f32_e32 v132, 0, v132
	v_exp_f32_e64 v134, -v132
	v_add_f32_e32 v15, v15, v132
	v_pk_add_f32 v[96:97], v[96:97], v[132:133] op_sel_hi:[1,0] neg_lo:[0,1] neg_hi:[0,1]
	v_pk_add_f32 v[98:99], v[98:99], v[132:133] op_sel_hi:[1,0] neg_lo:[0,1] neg_hi:[0,1]
	v_pk_add_f32 v[100:101], v[100:101], v[132:133] op_sel_hi:[1,0] neg_lo:[0,1] neg_hi:[0,1]
	v_pk_add_f32 v[102:103], v[102:103], v[132:133] op_sel_hi:[1,0] neg_lo:[0,1] neg_hi:[0,1]
	v_pk_add_f32 v[104:105], v[104:105], v[132:133] op_sel_hi:[1,0] neg_lo:[0,1] neg_hi:[0,1]
	v_pk_add_f32 v[106:107], v[106:107], v[132:133] op_sel_hi:[1,0] neg_lo:[0,1] neg_hi:[0,1]
	v_pk_add_f32 v[108:109], v[108:109], v[132:133] op_sel_hi:[1,0] neg_lo:[0,1] neg_hi:[0,1]
	v_pk_add_f32 v[110:111], v[110:111], v[132:133] op_sel_hi:[1,0] neg_lo:[0,1] neg_hi:[0,1]
	v_mul_f32_e32 v14, v14, v134
	v_pk_mul_f32 v[94:95], v[94:95], v[134:135] op_sel_hi:[1,0]
	v_pk_mul_f32 v[92:93], v[92:93], v[134:135] op_sel_hi:[1,0]
	v_pk_mul_f32 v[90:91], v[90:91], v[134:135] op_sel_hi:[1,0]
	v_pk_mul_f32 v[88:89], v[88:89], v[134:135] op_sel_hi:[1,0]
	v_pk_mul_f32 v[86:87], v[86:87], v[134:135] op_sel_hi:[1,0]
	v_pk_mul_f32 v[84:85], v[84:85], v[134:135] op_sel_hi:[1,0]
	v_pk_mul_f32 v[82:83], v[82:83], v[134:135] op_sel_hi:[1,0]
	v_pk_mul_f32 v[80:81], v[80:81], v[134:135] op_sel_hi:[1,0]
	v_pk_mul_f32 v[46:47], v[46:47], v[134:135] op_sel_hi:[1,0]
	v_pk_mul_f32 v[44:45], v[44:45], v[134:135] op_sel_hi:[1,0]
	v_pk_mul_f32 v[42:43], v[42:43], v[134:135] op_sel_hi:[1,0]
	v_pk_mul_f32 v[40:41], v[40:41], v[134:135] op_sel_hi:[1,0]
	v_pk_mul_f32 v[38:39], v[38:39], v[134:135] op_sel_hi:[1,0]
	v_pk_mul_f32 v[36:37], v[36:37], v[134:135] op_sel_hi:[1,0]
	v_pk_mul_f32 v[34:35], v[34:35], v[134:135] op_sel_hi:[1,0]
	v_pk_mul_f32 v[32:33], v[32:33], v[134:135] op_sel_hi:[1,0]

.LBB0_1952:
	s_waitcnt lgkmcnt(0)
	s_barrier
	v_add_u32_e32 v152, v231, v164
	ds_read_b128 v[48:51], v152
	ds_read_b128 v[52:55], v152 offset:32
	v_add_u32_e32 v153, v234, v228
	s_mov_b64 s[18:19], -1
	s_waitcnt vmcnt(3) lgkmcnt(1)
	v_mfma_f32_32x32x16_bf16 v[32:47], v[48:51], v[10:13], v[16:31]
	s_and_b64 vcc, exec, s[66:67]
	s_waitcnt vmcnt(2) lgkmcnt(0)
	v_mfma_f32_32x32x16_bf16 v[32:47], v[52:55], v[112:115], v[32:47]
	ds_read_b128 v[48:51], v152 offset:64
	ds_read_b128 v[52:55], v152 offset:96
	s_waitcnt vmcnt(1) lgkmcnt(1)
	v_mfma_f32_32x32x16_bf16 v[32:47], v[48:51], v[116:119], v[32:47]
	s_waitcnt vmcnt(0) lgkmcnt(0)
	v_mfma_f32_32x32x16_bf16 v[32:47], v[52:55], v[120:123], v[32:47]
	s_nop 11
	v_max_f32_e32 v1, v32, v33
	v_max3_f32 v1, v1, v34, v35
	v_max3_f32 v1, v1, v36, v37
	v_max3_f32 v1, v1, v38, v39
	v_max3_f32 v1, v1, v40, v41
	v_max3_f32 v1, v1, v42, v43
	v_max3_f32 v1, v1, v44, v45
	v_max3_f32 v1, v1, v46, v47
	v_mov_b32_e32 v14, v1
	s_nop 1
	v_permlane32_swap_b32_e32 v1, v14
	v_max_f32_e32 v14, v14, v14
	v_max_f32_e32 v1, v1, v1
	v_max_f32_e32 v15, v1, v14
	v_exp_f32_e64 v1, -v15
	v_sub_f32_e32 v14, v47, v15
	v_sub_f32_e32 v46, v46, v15
	v_sub_f32_e32 v45, v45, v15
	v_sub_f32_e32 v44, v44, v15
	v_sub_f32_e32 v43, v43, v15
	v_sub_f32_e32 v42, v42, v15
	v_sub_f32_e32 v41, v41, v15
	v_sub_f32_e32 v40, v40, v15
	v_sub_f32_e32 v39, v39, v15
	v_sub_f32_e32 v38, v38, v15
	v_sub_f32_e32 v37, v37, v15
	v_sub_f32_e32 v36, v36, v15
	v_sub_f32_e32 v35, v35, v15
	v_sub_f32_e32 v34, v34, v15
	v_sub_f32_e32 v33, v33, v15
	v_sub_f32_e32 v32, v32, v15
	v_exp_f32_e32 v53, v32
	v_exp_f32_e32 v52, v33
	v_exp_f32_e32 v55, v34
	v_exp_f32_e32 v54, v35
	v_exp_f32_e32 v57, v36
	v_exp_f32_e32 v56, v37
	v_exp_f32_e32 v59, v38
	v_exp_f32_e32 v58, v39
	v_exp_f32_e32 v61, v40
	v_exp_f32_e32 v60, v41
	v_exp_f32_e32 v63, v42
	v_exp_f32_e32 v62, v43
	v_exp_f32_e32 v97, v44
	v_exp_f32_e32 v96, v45
	v_exp_f32_e32 v99, v46
	v_exp_f32_e32 v98, v14
	v_cvt_pk_bf16_f32 v32, v53, v52
	v_cvt_pk_bf16_f32 v33, v55, v54
	v_cvt_pk_bf16_f32 v34, v57, v56
	v_cvt_pk_bf16_f32 v35, v59, v58
	v_cvt_pk_bf16_f32 v36, v61, v60
	v_cvt_pk_bf16_f32 v37, v63, v62
	v_cvt_pk_bf16_f32 v38, v97, v96
	v_cvt_pk_bf16_f32 v39, v99, v98
	ds_read_b64_tr_b16 v[40:41], v153 offset:4608
	ds_read_b64_tr_b16 v[42:43], v153 offset:5120
	v_mul_f32_e32 v64, 0, v1
	v_mov_b32_e32 v65, v64
	v_mov_b32_e32 v66, v64
	v_mov_b32_e32 v67, v64
	v_mov_b32_e32 v68, v64
	v_mov_b32_e32 v69, v64
	v_mov_b32_e32 v70, v64
	v_mov_b32_e32 v71, v64
	v_mov_b32_e32 v72, v64
	v_mov_b32_e32 v73, v64
	v_mov_b32_e32 v74, v64
	v_mov_b32_e32 v75, v64
	v_mov_b32_e32 v76, v64
	v_mov_b32_e32 v77, v64
	v_mov_b32_e32 v78, v64
	v_mov_b32_e32 v79, v64
	ds_read_b64_tr_b16 v[44:45], v153 offset:5632
	ds_read_b64_tr_b16 v[46:47], v153 offset:6144
	s_waitcnt lgkmcnt(2)
	v_mfma_f32_32x32x16_bf16 v[80:95], v[40:43], v[32:35], v[64:79]
	ds_read_b64_tr_b16 v[40:41], v153 offset:6656
	ds_read_b64_tr_b16 v[42:43], v153 offset:7168
	v_mov_b32_e32 v14, v64
	ds_read_b64_tr_b16 v[48:49], v153 offset:7680
	ds_read_b64_tr_b16 v[50:51], v153 offset:8192
	s_waitcnt lgkmcnt(0)
	s_waitcnt lgkmcnt(2)
	v_mfma_f32_32x32x16_bf16 v[64:79], v[40:43], v[32:35], v[64:79]
	v_add_f32_e64 v32, v52, 0
	v_add_f32_e64 v33, v53, 0
	v_add_f32_e64 v32, v54, v32
	v_add_f32_e64 v33, v55, v33
	v_add_f32_e64 v32, v56, v32
	v_add_f32_e64 v33, v57, v33
	v_pk_add_f32 v[32:33], v[58:59], v[32:33]
	v_mfma_f32_32x32x16_bf16 v[80:95], v[44:47], v[36:39], v[80:95]
	v_add_f32_e64 v32, v60, v32
	v_add_f32_e64 v33, v61, v33
	v_add_f32_e64 v32, v62, v32
	v_add_f32_e64 v33, v63, v33
	v_add_f32_e64 v32, v96, v32
	v_add_f32_e64 v33, v97, v33
	v_pk_add_f32 v[32:33], v[98:99], v[32:33]
	s_waitcnt lgkmcnt(0)
	v_mfma_f32_32x32x16_bf16 v[64:79], v[48:51], v[36:39], v[64:79]
	v_pk_add_f32 v[32:33], v[32:33], v[32:33] op_sel:[0,1] op_sel_hi:[1,0]
	s_nop 0
	v_mov_b32_e32 v33, v167
	v_pk_add_f32 v[148:149], v[14:15], v[32:33]
	s_cbranch_vccz .LBB0_1960
	s_nop 6
	v_mov_b64_e32 v[32:33], v[64:65]
	v_mov_b64_e32 v[48:49], v[80:81]
	v_add_u32_e32 v15, s91, v225
	s_mov_b32 s18, 1
	s_mov_b32 s19, 0
	v_mov_b64_e32 v[34:35], v[66:67]
	v_mov_b64_e32 v[36:37], v[68:69]
	v_mov_b64_e32 v[38:39], v[70:71]
	v_mov_b64_e32 v[40:41], v[72:73]
	v_mov_b64_e32 v[42:43], v[74:75]
	v_mov_b64_e32 v[44:45], v[76:77]
	v_mov_b64_e32 v[46:47], v[78:79]
	v_mov_b32_e32 v14, v148
	v_mov_b32_e32 v1, v149
	v_mov_b64_e32 v[50:51], v[82:83]
	v_mov_b64_e32 v[52:53], v[84:85]
	v_mov_b64_e32 v[54:55], v[86:87]
	v_mov_b64_e32 v[56:57], v[88:89]
	v_mov_b64_e32 v[58:59], v[90:91]
	v_mov_b64_e32 v[60:61], v[92:93]
	v_mov_b64_e32 v[62:63], v[94:95]
	s_branch .LBB0_1955

.LBB0_1957:
	s_waitcnt lgkmcnt(0)
	ds_read_b128 v[154:157], v152
	ds_read_b128 v[158:161], v152 offset:32
	v_xor_b32_e32 v96, 0x80000000, v1
	v_mov_b32_e32 v97, v96
	v_mov_b32_e32 v98, v96
	v_mov_b32_e32 v99, v96
	v_mov_b32_e32 v100, v96
	v_mov_b32_e32 v101, v96
	v_mov_b32_e32 v102, v96
	v_mov_b32_e32 v103, v96
	v_mov_b32_e32 v104, v96
	v_mov_b32_e32 v105, v96
	v_mov_b32_e32 v106, v96
	v_mov_b32_e32 v107, v96
	v_mov_b32_e32 v108, v96
	v_mov_b32_e32 v109, v96
	v_mov_b32_e32 v110, v96
	v_mov_b32_e32 v111, v96
	s_waitcnt lgkmcnt(1)
	s_nop 0
	v_mfma_f32_32x32x16_bf16 v[96:111], v[154:157], v[10:13], v[96:111]
	s_waitcnt lgkmcnt(0)
	v_mfma_f32_32x32x16_bf16 v[96:111], v[158:161], v[112:115], v[96:111]
	ds_read_b128 v[154:157], v152 offset:64
	ds_read_b128 v[158:161], v152 offset:96
	s_waitcnt lgkmcnt(1)
	v_mfma_f32_32x32x16_bf16 v[96:111], v[154:157], v[116:119], v[96:111]
	s_waitcnt lgkmcnt(0)
	v_mfma_f32_32x32x16_bf16 v[96:111], v[158:161], v[120:123], v[96:111]
	s_nop 11
	v_max_f32_e32 v154, v96, v97
	v_max3_f32 v154, v154, v98, v99
	v_max3_f32 v154, v154, v100, v101
	v_max3_f32 v154, v154, v102, v103
	v_max3_f32 v154, v154, v104, v105
	v_max3_f32 v154, v154, v106, v107
	v_max3_f32 v154, v154, v108, v109
	v_max3_f32 v154, v154, v110, v111
	v_mov_b32_e32 v155, v154
	s_nop 1
	v_permlane32_swap_b32_e32 v154, v155
	v_max_f32_e32 v154, v154, v155
	v_cmp_lt_f32_e32 vcc, s88, v154
	s_cbranch_vccz .LBB0_1954
	v_max_f32_e32 v154, v154, v154
	v_max_f32_e32 v154, 0, v154
	v_exp_f32_e64 v156, -v154
	v_add_f32_e32 v1, v1, v154
	v_pk_add_f32 v[96:97], v[96:97], v[154:155] op_sel_hi:[1,0] neg_lo:[0,1] neg_hi:[0,1]
	v_pk_add_f32 v[98:99], v[98:99], v[154:155] op_sel_hi:[1,0] neg_lo:[0,1] neg_hi:[0,1]
	v_pk_add_f32 v[100:101], v[100:101], v[154:155] op_sel_hi:[1,0] neg_lo:[0,1] neg_hi:[0,1]
	v_pk_add_f32 v[102:103], v[102:103], v[154:155] op_sel_hi:[1,0] neg_lo:[0,1] neg_hi:[0,1]
	v_pk_add_f32 v[104:105], v[104:105], v[154:155] op_sel_hi:[1,0] neg_lo:[0,1] neg_hi:[0,1]
	v_pk_add_f32 v[106:107], v[106:107], v[154:155] op_sel_hi:[1,0] neg_lo:[0,1] neg_hi:[0,1]
	v_pk_add_f32 v[108:109], v[108:109], v[154:155] op_sel_hi:[1,0] neg_lo:[0,1] neg_hi:[0,1]
	v_pk_add_f32 v[110:111], v[110:111], v[154:155] op_sel_hi:[1,0] neg_lo:[0,1] neg_hi:[0,1]
	v_mul_f32_e32 v14, v14, v156
	v_pk_mul_f32 v[62:63], v[62:63], v[156:157] op_sel_hi:[1,0]
	v_pk_mul_f32 v[60:61], v[60:61], v[156:157] op_sel_hi:[1,0]
	v_pk_mul_f32 v[58:59], v[58:59], v[156:157] op_sel_hi:[1,0]
	v_pk_mul_f32 v[56:57], v[56:57], v[156:157] op_sel_hi:[1,0]
	v_pk_mul_f32 v[54:55], v[54:55], v[156:157] op_sel_hi:[1,0]
	v_pk_mul_f32 v[52:53], v[52:53], v[156:157] op_sel_hi:[1,0]
	v_pk_mul_f32 v[50:51], v[50:51], v[156:157] op_sel_hi:[1,0]
	v_pk_mul_f32 v[48:49], v[48:49], v[156:157] op_sel_hi:[1,0]
	v_pk_mul_f32 v[46:47], v[46:47], v[156:157] op_sel_hi:[1,0]
	v_pk_mul_f32 v[44:45], v[44:45], v[156:157] op_sel_hi:[1,0]
	v_pk_mul_f32 v[42:43], v[42:43], v[156:157] op_sel_hi:[1,0]
	v_pk_mul_f32 v[40:41], v[40:41], v[156:157] op_sel_hi:[1,0]
	v_pk_mul_f32 v[38:39], v[38:39], v[156:157] op_sel_hi:[1,0]
	v_pk_mul_f32 v[36:37], v[36:37], v[156:157] op_sel_hi:[1,0]
	v_pk_mul_f32 v[34:35], v[34:35], v[156:157] op_sel_hi:[1,0]
	v_pk_mul_f32 v[32:33], v[32:33], v[156:157] op_sel_hi:[1,0]
	s_branch .LBB0_1954
